# P12 band attention: skewed chunk schedule (wave w works on chunk kc + (w>>1)), 5 LDS tile slots, 9 loop steps per 256-row item instead of 12
# speedup vs baseline: 1.0103x; 1.0103x over previous
.LBB0_1041:
	s_or_b64 exec, exec, s[0:1]
	s_ashr_i32 s0, s3, 5
	s_add_i32 s0, s0, s4
	s_and_b32 s8, s5, 15
	s_ashr_i32 s1, s0, 31
	s_lshl_b64 s[28:29], s[0:1], 12
	s_lshl_b32 s1, s8, 8
	s_lshl_b32 s11, s8, 2
	s_or_b32 s3, s28, s1
	s_add_u32 s22, s3, s14
	s_addc_u32 s23, s29, s20
	s_mul_i32 s3, s23, 0x1400
	s_mul_hi_u32 s4, s22, 0x1400
	s_add_i32 s4, s4, s3
	s_mul_i32 s3, s22, 0x1400
	s_add_u32 s5, s60, s3
	s_addc_u32 s4, s61, s4
	s_lshl_b32 s2, s2, 6
	s_ashr_i32 s3, s2, 31
	s_lshl_b64 s[24:25], s[2:3], 1
	s_add_u32 s2, s5, s24
	s_addc_u32 s3, s4, s25
	s_add_u32 s4, s94, s24
	s_addc_u32 s5, s19, s25
	s_add_u32 s6, s31, s24
	s_addc_u32 s7, s33, s25
	s_add_i32 s9, s11, -8
	s_cmp_gt_u32 s8, 1
	s_cselect_b32 s30, s9, 0
	v_lshl_add_u64 v[0:1], s[2:3], 0, v[152:153]
	v_mov_b32_e32 v131, v153
	s_lshl_b32 s8, s30, 6
	v_lshl_add_u64 v[8:9], v[0:1], 0, v[130:131]
	s_mov_b64 s[2:3], 0x14000
	s_ashr_i32 s9, s8, 31
	v_lshl_add_u64 v[32:33], s[28:29], 0, v[114:115]
	v_lshl_add_u64 v[12:13], v[8:9], 0, s[2:3]
	s_mov_b32 s2, 0x14000
	v_lshl_add_u64 v[10:11], v[32:33], 0, s[8:9]
	global_load_dwordx4 v[0:3], v[8:9], off
	global_load_dwordx4 v[4:7], v[8:9], off offset:64
	v_add_co_u32_e32 v8, vcc, s2, v8
	v_mad_u64_u32 v[14:15], s[2:3], v10, s40, 0
	v_mad_i32_i24 v11, v11, s40, v15
	v_or_b32_e32 v10, v14, v112
	v_lshlrev_b64 v[10:11], 1, v[10:11]
	v_addc_co_u32_e32 v9, vcc, 0, v9, vcc
	v_lshl_add_u64 v[14:15], s[4:5], 0, v[10:11]
	v_lshl_add_u64 v[10:11], s[6:7], 0, v[10:11]
	v_mov_b32_e32 v230, v14
	v_mov_b32_e32 v231, v15
	v_mov_b32_e32 v232, v10
	v_mov_b32_e32 v233, v11
	s_add_i32 s2, s11, 4
	s_cmp_ge_u32 s11, 8
	s_cbranch_scc0 .Lbs_noskew
	global_load_dwordx4 v[206:209], v[230:231], off
	global_load_dwordx4 v[210:213], v[232:233], off
	v_add_co_u32_e32 v230, vcc, 0x50000, v230
	s_nop 1
	v_addc_co_u32_e32 v231, vcc, 0, v231, vcc
	v_add_co_u32_e32 v232, vcc, 0x50000, v232
	s_nop 1
	v_addc_co_u32_e32 v233, vcc, 0, v233, vcc
	global_load_dwordx4 v[214:217], v[230:231], off
	global_load_dwordx4 v[218:221], v[232:233], off
	v_add_co_u32_e32 v230, vcc, 0x50000, v230
	s_nop 1
	v_addc_co_u32_e32 v231, vcc, 0, v231, vcc
	v_add_co_u32_e32 v232, vcc, 0x50000, v232
	s_nop 1
	v_addc_co_u32_e32 v233, vcc, 0, v233, vcc
	global_load_dwordx4 v[222:225], v[230:231], off
	global_load_dwordx4 v[226:229], v[232:233], off
	v_add_co_u32_e32 v230, vcc, 0x50000, v230
	s_nop 1
	v_addc_co_u32_e32 v231, vcc, 0, v231, vcc
	v_add_co_u32_e32 v232, vcc, 0x50000, v232
	s_nop 1
	v_addc_co_u32_e32 v233, vcc, 0, v233, vcc
.Lbs_noskew:
	global_load_dwordx4 v[16:19], v[230:231], off
	global_load_dwordx4 v[20:23], v[232:233], off
	v_add_co_u32_e32 v230, vcc, 0x50000, v230
	s_nop 1
	v_addc_co_u32_e32 v231, vcc, 0, v231, vcc
	v_add_co_u32_e32 v232, vcc, 0x50000, v232
	s_nop 1
	v_addc_co_u32_e32 v233, vcc, 0, v233, vcc
	global_load_dwordx4 v[8:11], v[8:9], off
	global_load_dwordx4 v[12:15], v[12:13], off offset:64
	global_load_dwordx4 v[24:27], v[230:231], off
	global_load_dwordx4 v[28:31], v[232:233], off
	s_cmp_ge_u32 s11, 8
	s_cbranch_scc0 .Lbs_nopre
	s_waitcnt vmcnt(6)
	s_add_i32 s4, s30, 0
	s_mul_hi_u32 s6, s4, 0x33333334
	s_mul_i32 s6, s6, 5
	s_sub_i32 s4, s4, s6
	s_mul_i32 s6, s4, 0x6c00
	s_add_i32 s6, s6, 0xffffc800
	s_mul_i32 s5, s4, 0x2400
	s_cmp_gt_u32 s4, 1
	s_cselect_b32 s5, s6, s5
	v_add_u32_e32 v234, s5, v123
	ds_write_b128 v234, v[206:209]
	ds_write_b128 v234, v[210:213] offset:18432
	s_add_i32 s4, s30, 1
	s_mul_hi_u32 s6, s4, 0x33333334
	s_mul_i32 s6, s6, 5
	s_sub_i32 s4, s4, s6
	s_mul_i32 s6, s4, 0x6c00
	s_add_i32 s6, s6, 0xffffc800
	s_mul_i32 s5, s4, 0x2400
	s_cmp_gt_u32 s4, 1
	s_cselect_b32 s5, s6, s5
	v_add_u32_e32 v234, s5, v123
	ds_write_b128 v234, v[214:217]
	ds_write_b128 v234, v[218:221] offset:18432
	s_add_i32 s4, s30, 2
	s_mul_hi_u32 s6, s4, 0x33333334
	s_mul_i32 s6, s6, 5
	s_sub_i32 s4, s4, s6
	s_mul_i32 s6, s4, 0x6c00
	s_add_i32 s6, s6, 0xffffc800
	s_mul_i32 s5, s4, 0x2400
	s_cmp_gt_u32 s4, 1
	s_cselect_b32 s5, s6, s5
	v_add_u32_e32 v234, s5, v123
	ds_write_b128 v234, v[222:225]
	ds_write_b128 v234, v[226:229] offset:18432
.Lbs_nopre:
.LBB0_1043:
	s_add_i32 s3, s11, s13
	s_add_i32 s4, s3, -8
	s_cmp_gt_i32 s3, 7
	s_cselect_b32 s27, s4, 0
	v_add_u32_e32 v32, s1, v144
	s_sub_i32 s28, s21, s11
	s_mul_hi_i32 s1, s0, 0x1400000
	s_mul_i32 s0, s0, 0x1400000
	s_add_u32 s0, s24, s0
	s_addc_u32 s1, s25, s1
	v_subrev_u32_e32 v133, s8, v32
	s_cmp_ge_u32 s11, 8
	s_cselect_b32 s4, s13, 0
	s_sub_i32 s27, s27, s4
	s_sub_i32 s3, s3, s4
	s_add_i32 s28, s28, s4
	s_lshl_b32 s5, s4, 6
	v_subrev_u32_e32 v133, s5, v133
	s_add_i32 s5, s30, 9
	s_cmp_ge_u32 s11, 8
	s_cselect_b32 s2, s5, s2
	v_add_u32_e32 v34, s8, v114
	v_mov_b64_e32 v[32:33], s[0:1]
	s_movk_i32 s0, 0x1400
	v_mad_i64_i32 v[32:33], s[0:1], v34, s0, v[32:33]
	v_mov_b32_e32 v34, v153
	v_mov_b32_e32 v35, v153
	v_lshl_add_u64 v[140:141], v[128:129], 0, v[32:33]
	s_cmp_ge_u32 s11, 8
	s_cselect_b32 s4, 0xf0000, 0
	s_mov_b32 s5, 0
	v_lshl_add_u64 v[140:141], v[140:141], 0, s[4:5]
	v_mov_b32_e32 v32, v153
	v_mov_b32_e32 v33, v153
	v_mov_b64_e32 v[38:39], v[34:35]
	v_mov_b64_e32 v[50:51], v[34:35]
	v_mov_b64_e32 v[42:43], v[34:35]
	v_mov_b64_e32 v[46:47], v[34:35]
	v_mov_b64_e32 v[54:55], v[34:35]
	v_mov_b64_e32 v[62:63], v[34:35]
	v_mov_b64_e32 v[58:59], v[34:35]
	v_mov_b32_e32 v131, 0
	v_mov_b32_e32 v137, 0xf149f2ca
	v_mov_b64_e32 v[36:37], v[32:33]
	v_mov_b64_e32 v[48:49], v[32:33]
	v_mov_b64_e32 v[40:41], v[32:33]
	v_mov_b64_e32 v[44:45], v[32:33]
	v_mov_b64_e32 v[52:53], v[32:33]
	v_mov_b64_e32 v[60:61], v[32:33]
	v_mov_b64_e32 v[56:57], v[32:33]
	v_mov_b32_e32 v139, 0xf149f2ca
	v_mov_b32_e32 v135, 0
.LBB0_1044:
	s_add_i32 s29, s30, 2
	s_cmp_ge_i32 s29, s2
	s_cselect_b64 s[0:1], -1, 0
	s_and_b64 vcc, exec, s[0:1]
	s_cmp_ge_u32 s11, 8
	s_cselect_b32 s4, 3, 0
	s_add_i32 s4, s4, s30
	s_mul_hi_u32 s6, s4, 0x33333334
	s_mul_i32 s6, s6, 5
	s_sub_i32 s4, s4, s6
	s_mul_i32 s6, s4, 0x6c00
	s_add_i32 s6, s6, 0xffffc800
	s_mul_i32 s5, s4, 0x2400
	s_cmp_gt_u32 s4, 1
	s_cselect_b32 s5, s6, s5
	v_add_u32_e32 v234, s5, v123
	s_waitcnt vmcnt(3)
	ds_write_b128 v234, v[16:19]
	s_waitcnt vmcnt(2)
	ds_write_b128 v234, v[20:23] offset:18432
	s_waitcnt lgkmcnt(0)
	s_barrier
	v_add_co_u32_e32 v20, vcc, 0xfffb0000, v140
	s_nop 1
	v_addc_co_u32_e32 v21, vcc, -1, v141, vcc
	global_load_dwordx4 v[16:19], v[20:21], off offset:-1536
	s_nop 0
	global_load_dwordx4 v[20:23], v[20:21], off
	s_cmp_ge_u32 s11, 8
	s_cselect_b32 s4, s13, 0
	s_add_i32 s4, s4, s30
	s_mul_hi_u32 s6, s4, 0x33333334
	s_mul_i32 s6, s6, 5
	s_sub_i32 s4, s4, s6
	s_mul_i32 s6, s4, 0x6c00
	s_add_i32 s6, s6, 0xffffc800
	s_mul_i32 s5, s4, 0x2400
	s_cmp_gt_u32 s4, 1
	s_cselect_b32 s5, s6, s5
	v_add_u32_e32 v235, s5, v125
	v_add_u32_e32 v236, s5, v143
.LBB0_1046:
	s_cmp_lt_i32 s30, s27
	s_cselect_b64 s[4:5], -1, 0
	s_cmp_gt_i32 s30, s3
	s_cselect_b64 s[6:7], -1, 0
	s_or_b64 s[4:5], s[4:5], s[6:7]
	s_and_b64 vcc, exec, s[4:5]
	s_cbranch_vccnz .LBB0_1056
	ds_read_b128 v[64:67], v235
	ds_read_b128 v[72:75], v235 offset:64
	s_add_i32 s4, s28, s30
	s_add_i32 s4, s4, 8
	s_cmp_lt_i32 s4, 6
	s_cselect_b64 s[4:5], -1, 0
	s_mov_b64 s[8:9], -1
	s_and_b64 vcc, exec, s[4:5]
	s_waitcnt lgkmcnt(1)
	v_mfma_f32_16x16x32_bf16 v[68:71], v[64:67], v[0:3], 0
	ds_read_b128 v[76:79], v235 offset:4672
	ds_read_b128 v[80:83], v235 offset:6976
	v_mfma_f32_16x16x32_bf16 v[64:67], v[64:67], v[8:11], 0
	s_waitcnt lgkmcnt(2)
	v_mfma_f32_16x16x32_bf16 v[84:87], v[72:75], v[12:15], v[64:67]
	v_mfma_f32_16x16x32_bf16 v[108:111], v[72:75], v[4:7], v[68:71]
	s_nop 4
	ds_read_b128 v[64:67], v235 offset:2304
	ds_read_b128 v[72:75], v235 offset:2368
	s_waitcnt lgkmcnt(1)
	v_mfma_f32_16x16x32_bf16 v[68:71], v[64:67], v[0:3], 0
	v_mfma_f32_16x16x32_bf16 v[64:67], v[64:67], v[8:11], 0
	s_waitcnt lgkmcnt(0)
	v_mfma_f32_16x16x32_bf16 v[104:107], v[72:75], v[4:7], v[68:71]
	v_mfma_f32_16x16x32_bf16 v[72:75], v[72:75], v[12:15], v[64:67]
	s_nop 4
	ds_read_b128 v[64:67], v235 offset:4608
	s_waitcnt lgkmcnt(0)
	v_mfma_f32_16x16x32_bf16 v[68:71], v[64:67], v[0:3], 0
	v_mfma_f32_16x16x32_bf16 v[64:67], v[64:67], v[8:11], 0
	v_mfma_f32_16x16x32_bf16 v[100:103], v[76:79], v[4:7], v[68:71]
	v_mfma_f32_16x16x32_bf16 v[68:71], v[76:79], v[12:15], v[64:67]
	s_nop 5
	ds_read_b128 v[64:67], v235 offset:6912
	s_waitcnt lgkmcnt(0)
	v_mfma_f32_16x16x32_bf16 v[76:79], v[64:67], v[0:3], 0
	v_mfma_f32_16x16x32_bf16 v[64:67], v[64:67], v[8:11], 0
	v_mfma_f32_16x16x32_bf16 v[96:99], v[80:83], v[4:7], v[76:79]
	v_mfma_f32_16x16x32_bf16 v[64:67], v[80:83], v[12:15], v[64:67]
	s_cbranch_vccz .LBB0_1072
	s_nop 3
	v_max3_f32 v77, v108, v109, v110
	v_max3_f32 v78, v104, v105, v106
	v_max3_f32 v77, v77, v111, v107
	v_max3_f32 v77, v77, v78, s95
	v_max3_f32 v78, v100, v101, v102
	v_max3_f32 v79, v96, v97, v98
	v_max3_f32 v78, v78, v103, v99
	v_max3_f32 v77, v77, v78, v79
	v_mov_b32_e32 v78, v77
	s_nop 1
	v_permlane16_swap_b32_e32 v77, v78
	ds_read_b32 v76, v153 offset:37628
	v_max_f32_e32 v77, v77, v78
	v_mov_b32_e32 v78, v77
	s_nop 1
	v_permlane32_swap_b32_e32 v77, v78
	v_max_f32_e32 v77, v77, v78
	s_waitcnt lgkmcnt(0)
	v_fmamk_f32 v77, v77, 0x3e38aa3b, v76
	v_sub_f32_e32 v78, v77, v139
	v_cmp_ge_f32_e32 vcc, s97, v78
	v_max_f32_e32 v78, v139, v139
	v_max_f32_e32 v77, v78, v77
	s_cmp_lg_u64 vcc, exec
	v_sub_f32_e32 v78, v139, v77
	s_cselect_b64 s[6:7], -1, 0
	v_exp_f32_e32 v78, v78
	v_cndmask_b32_e64 v145, v139, v77, s[6:7]
	s_mov_b32 s100, 0x3e38aa3b
	v_sub_f32_e32 v170, v76, v145
	v_cndmask_b32_e64 v142, 1.0, v78, s[6:7]
	v_pk_fma_f32 v[76:77], v[108:109], s[100:101], v[170:171] op_sel_hi:[1,0,0]
	v_pk_fma_f32 v[78:79], v[110:111], s[100:101], v[170:171] op_sel_hi:[1,0,0]
	v_pk_fma_f32 v[80:81], v[104:105], s[100:101], v[170:171] op_sel_hi:[1,0,0]
	v_pk_fma_f32 v[82:83], v[106:107], s[100:101], v[170:171] op_sel_hi:[1,0,0]
	v_pk_fma_f32 v[88:89], v[100:101], s[100:101], v[170:171] op_sel_hi:[1,0,0]
	v_pk_fma_f32 v[90:91], v[102:103], s[100:101], v[170:171] op_sel_hi:[1,0,0]
	v_pk_fma_f32 v[92:93], v[96:97], s[100:101], v[170:171] op_sel_hi:[1,0,0]
	v_pk_fma_f32 v[94:95], v[98:99], s[100:101], v[170:171] op_sel_hi:[1,0,0]
	v_exp_f32_e32 v76, v76
	v_exp_f32_e32 v77, v77
	v_exp_f32_e32 v78, v78
	v_exp_f32_e32 v79, v79
	v_exp_f32_e32 v80, v80
	v_exp_f32_e32 v81, v81
	v_exp_f32_e32 v82, v82
	v_exp_f32_e32 v83, v83
	v_exp_f32_e32 v88, v88
	v_exp_f32_e32 v89, v89
	v_exp_f32_e32 v90, v90
	v_exp_f32_e32 v91, v91
	v_exp_f32_e32 v92, v92
	v_exp_f32_e32 v93, v93
	v_exp_f32_e32 v94, v94
	v_exp_f32_e32 v95, v95
	v_pk_add_f32 v[172:173], v[76:77], v[78:79]
	v_pk_add_f32 v[174:175], v[80:81], v[82:83]
	v_pk_add_f32 v[172:173], v[172:173], v[88:89]
	v_pk_add_f32 v[174:175], v[174:175], v[90:91]
	v_pk_add_f32 v[172:173], v[172:173], v[92:93]
	v_pk_add_f32 v[174:175], v[174:175], v[94:95]
	v_pk_add_f32 v[172:173], v[172:173], v[174:175]
	v_add_f32_e32 v147, v172, v173
	s_cbranch_execz .LBB0_1073

.LBB0_1055:
	v_cvt_pk_bf16_f32 v74, v80, v81
	v_cvt_pk_bf16_f32 v75, v82, v83
	ds_read_b64_tr_b16 v[82:83], v236 offset:20736
	ds_read_b64_tr_b16 v[80:81], v236 offset:18432
	ds_read_b64_tr_b16 v[84:85], v236 offset:18464
	v_cvt_pk_bf16_f32 v72, v76, v77
	v_cvt_pk_bf16_f32 v73, v78, v79
	v_cvt_pk_bf16_f32 v76, v96, v97
	v_cvt_pk_bf16_f32 v77, v98, v99
	v_cvt_pk_bf16_f32 v78, v100, v101
	v_cvt_pk_bf16_f32 v79, v102, v103
	s_waitcnt lgkmcnt(1)
	v_mfma_f32_16x16x32_bf16 v[56:59], v[80:83], v[72:75], v[56:59]
	ds_read_b64_tr_b16 v[86:87], v236 offset:20768
	v_cvt_pk_bf16_f32 v68, v88, v89
	v_cvt_pk_bf16_f32 v69, v90, v91
	v_mfma_f32_16x16x32_bf16 v[40:43], v[80:83], v[76:79], v[40:43]
	ds_read_b64_tr_b16 v[80:81], v236 offset:18496
	ds_read_b64_tr_b16 v[82:83], v236 offset:20800
	v_cvt_pk_bf16_f32 v70, v92, v93
	v_cvt_pk_bf16_f32 v71, v94, v95
	s_waitcnt lgkmcnt(0)
	v_mfma_f32_16x16x32_bf16 v[52:55], v[80:83], v[72:75], v[52:55]
	v_cvt_pk_bf16_f32 v64, v104, v105
	v_cvt_pk_bf16_f32 v65, v106, v107
	v_cvt_pk_bf16_f32 v66, v108, v109
	v_mfma_f32_16x16x32_bf16 v[36:39], v[80:83], v[76:79], v[36:39]
	ds_read_b64_tr_b16 v[80:81], v236 offset:18528
	ds_read_b64_tr_b16 v[82:83], v236 offset:20832
	v_cvt_pk_bf16_f32 v67, v110, v111
	v_add_f32_e32 v135, v147, v135
	v_mfma_f32_16x16x32_bf16 v[60:63], v[84:87], v[72:75], v[60:63]
	v_add_f32_e32 v131, v139, v131
	s_waitcnt lgkmcnt(0)
	v_mfma_f32_16x16x32_bf16 v[44:47], v[80:83], v[72:75], v[44:47]
	ds_read_b64_tr_b16 v[72:73], v236 offset:23040
	ds_read_b64_tr_b16 v[74:75], v236 offset:25344
	s_waitcnt lgkmcnt(0)
	v_mfma_f32_16x16x32_bf16 v[56:59], v[72:75], v[68:71], v[56:59]
	v_mfma_f32_16x16x32_bf16 v[40:43], v[72:75], v[64:67], v[40:43]
	ds_read_b64_tr_b16 v[72:73], v236 offset:23072
	ds_read_b64_tr_b16 v[74:75], v236 offset:25376
	v_mfma_f32_16x16x32_bf16 v[48:51], v[84:87], v[76:79], v[48:51]
	s_waitcnt lgkmcnt(0)
	v_mfma_f32_16x16x32_bf16 v[60:63], v[72:75], v[68:71], v[60:63]
	v_mfma_f32_16x16x32_bf16 v[48:51], v[72:75], v[64:67], v[48:51]
	ds_read_b64_tr_b16 v[72:73], v236 offset:23104
	ds_read_b64_tr_b16 v[74:75], v236 offset:25408
	s_waitcnt lgkmcnt(0)
	v_mfma_f32_16x16x32_bf16 v[52:55], v[72:75], v[68:71], v[52:55]
	v_mfma_f32_16x16x32_bf16 v[36:39], v[72:75], v[64:67], v[36:39]
	ds_read_b64_tr_b16 v[72:73], v236 offset:23136
	ds_read_b64_tr_b16 v[74:75], v236 offset:25440
	v_mfma_f32_16x16x32_bf16 v[32:35], v[80:83], v[76:79], v[32:35]
	s_waitcnt lgkmcnt(0)
	v_mfma_f32_16x16x32_bf16 v[44:47], v[72:75], v[68:71], v[44:47]
	v_mfma_f32_16x16x32_bf16 v[32:35], v[72:75], v[64:67], v[32:35]
	s_add_i32 s4, s30, 1
	s_cmp_ge_i32 s4, s2
	s_cbranch_scc0 .LBB0_1057
	s_branch .LBB0_1069

.LBB0_1057:
	s_add_i32 s5, s30, 3
	s_cmp_ge_i32 s5, s2
	s_cmp_ge_u32 s11, 8
	s_cselect_b32 s5, 4, 1
	s_add_i32 s5, s5, s30
	s_mul_hi_u32 s7, s5, 0x33333334
	s_mul_i32 s7, s7, 5
	s_sub_i32 s5, s5, s7
	s_mul_i32 s7, s5, 0x6c00
	s_add_i32 s7, s7, 0xffffc800
	s_mul_i32 s6, s5, 0x2400
	s_cmp_gt_u32 s5, 1
	s_cselect_b32 s6, s7, s6
	s_add_i32 s6, s6, 0xffffdc00
	v_add_u32_e32 v234, s6, v123
	s_waitcnt vmcnt(3)
	ds_write_b128 v234, v[24:27] offset:9216
	s_waitcnt vmcnt(2)
	ds_write_b128 v234, v[28:31] offset:27648
	s_waitcnt lgkmcnt(0)
	s_barrier
	global_load_dwordx4 v[24:27], v[140:141], off offset:-1536
	global_load_dwordx4 v[28:31], v[140:141], off
	s_cmp_ge_u32 s11, 8
	s_cselect_b32 s5, s13, 0
	s_add_i32 s5, s5, s30
	s_add_i32 s5, s5, 1
	s_mul_hi_u32 s7, s5, 0x33333334
	s_mul_i32 s7, s7, 5
	s_sub_i32 s5, s5, s7
	s_mul_i32 s7, s5, 0x6c00
	s_add_i32 s7, s7, 0xffffc800
	s_mul_i32 s6, s5, 0x2400
	s_cmp_gt_u32 s5, 1
	s_cselect_b32 s6, s7, s6
	s_add_i32 s6, s6, 0xffffdc00
	v_add_u32_e32 v235, s6, v125
	v_add_u32_e32 v236, s6, v143
.LBB0_1059:
	s_cmp_lt_i32 s4, s27
	s_cselect_b64 s[4:5], -1, 0
	s_cmp_ge_i32 s30, s3
	s_cselect_b64 s[6:7], -1, 0
	s_or_b64 s[4:5], s[6:7], s[4:5]
	s_and_b64 vcc, exec, s[4:5]
	s_cbranch_vccnz .LBB0_1069
	ds_read_b128 v[64:67], v235 offset:9216
	ds_read_b128 v[72:75], v235 offset:9280
	s_add_i32 s4, s28, s30
	s_add_i32 s4, s4, 9
	s_cmp_lt_i32 s4, 6
	s_cselect_b64 s[4:5], -1, 0
	s_mov_b64 s[8:9], -1
	s_and_b64 vcc, exec, s[4:5]
	s_waitcnt lgkmcnt(1)
	v_mfma_f32_16x16x32_bf16 v[68:71], v[64:67], v[0:3], 0
	ds_read_b128 v[76:79], v235 offset:13888
	ds_read_b128 v[80:83], v235 offset:16192
	v_mfma_f32_16x16x32_bf16 v[64:67], v[64:67], v[8:11], 0
	s_waitcnt lgkmcnt(2)
	v_mfma_f32_16x16x32_bf16 v[84:87], v[72:75], v[12:15], v[64:67]
	v_mfma_f32_16x16x32_bf16 v[108:111], v[72:75], v[4:7], v[68:71]
	s_nop 4
	ds_read_b128 v[64:67], v235 offset:11520
	ds_read_b128 v[72:75], v235 offset:11584
	s_waitcnt lgkmcnt(1)
	v_mfma_f32_16x16x32_bf16 v[68:71], v[64:67], v[0:3], 0
	v_mfma_f32_16x16x32_bf16 v[64:67], v[64:67], v[8:11], 0
	s_waitcnt lgkmcnt(0)
	v_mfma_f32_16x16x32_bf16 v[104:107], v[72:75], v[4:7], v[68:71]
	v_mfma_f32_16x16x32_bf16 v[72:75], v[72:75], v[12:15], v[64:67]
	s_nop 4
	ds_read_b128 v[64:67], v235 offset:13824
	s_waitcnt lgkmcnt(0)
	v_mfma_f32_16x16x32_bf16 v[68:71], v[64:67], v[0:3], 0
	v_mfma_f32_16x16x32_bf16 v[64:67], v[64:67], v[8:11], 0
	v_mfma_f32_16x16x32_bf16 v[100:103], v[76:79], v[4:7], v[68:71]
	v_mfma_f32_16x16x32_bf16 v[68:71], v[76:79], v[12:15], v[64:67]
	s_nop 5
	ds_read_b128 v[64:67], v235 offset:16128
	s_waitcnt lgkmcnt(0)
	v_mfma_f32_16x16x32_bf16 v[76:79], v[64:67], v[0:3], 0
	v_mfma_f32_16x16x32_bf16 v[64:67], v[64:67], v[8:11], 0
	v_mfma_f32_16x16x32_bf16 v[96:99], v[80:83], v[4:7], v[76:79]
	v_mfma_f32_16x16x32_bf16 v[64:67], v[80:83], v[12:15], v[64:67]
	s_cbranch_vccz .LBB0_1076
	s_nop 3
	v_max3_f32 v77, v108, v109, v110
	v_max3_f32 v78, v104, v105, v106
	v_max3_f32 v77, v77, v111, v107
	v_max3_f32 v77, v77, v78, s95
	v_max3_f32 v78, v100, v101, v102
	v_max3_f32 v79, v96, v97, v98
	v_max3_f32 v78, v78, v103, v99
	v_max3_f32 v77, v77, v78, v79
	v_mov_b32_e32 v78, v77
	s_nop 1
	v_permlane16_swap_b32_e32 v77, v78
	ds_read_b32 v76, v153 offset:37628
	v_max_f32_e32 v77, v77, v78
	v_mov_b32_e32 v78, v77
	s_nop 1
	v_permlane32_swap_b32_e32 v77, v78
	v_max_f32_e32 v77, v77, v78
	s_waitcnt lgkmcnt(0)
	v_fmamk_f32 v77, v77, 0x3e38aa3b, v76
	v_sub_f32_e32 v78, v77, v145
	v_cmp_ge_f32_e32 vcc, s97, v78
	v_max_f32_e32 v78, v145, v145
	v_max_f32_e32 v77, v78, v77
	s_cmp_lg_u64 vcc, exec
	v_sub_f32_e32 v78, v145, v77
	s_cselect_b64 s[6:7], -1, 0
	v_exp_f32_e32 v78, v78
	v_cndmask_b32_e64 v139, v145, v77, s[6:7]
	s_mov_b32 s100, 0x3e38aa3b
	v_sub_f32_e32 v170, v76, v139
	v_cndmask_b32_e64 v142, 1.0, v78, s[6:7]
	v_pk_fma_f32 v[76:77], v[108:109], s[100:101], v[170:171] op_sel_hi:[1,0,0]
	v_pk_fma_f32 v[78:79], v[110:111], s[100:101], v[170:171] op_sel_hi:[1,0,0]
	v_pk_fma_f32 v[80:81], v[104:105], s[100:101], v[170:171] op_sel_hi:[1,0,0]
	v_pk_fma_f32 v[82:83], v[106:107], s[100:101], v[170:171] op_sel_hi:[1,0,0]
	v_pk_fma_f32 v[88:89], v[100:101], s[100:101], v[170:171] op_sel_hi:[1,0,0]
	v_pk_fma_f32 v[90:91], v[102:103], s[100:101], v[170:171] op_sel_hi:[1,0,0]
	v_pk_fma_f32 v[92:93], v[96:97], s[100:101], v[170:171] op_sel_hi:[1,0,0]
	v_pk_fma_f32 v[94:95], v[98:99], s[100:101], v[170:171] op_sel_hi:[1,0,0]
	v_exp_f32_e32 v76, v76
	v_exp_f32_e32 v77, v77
	v_exp_f32_e32 v78, v78
	v_exp_f32_e32 v79, v79
	v_exp_f32_e32 v80, v80
	v_exp_f32_e32 v81, v81
	v_exp_f32_e32 v82, v82
	v_exp_f32_e32 v83, v83
	v_exp_f32_e32 v88, v88
	v_exp_f32_e32 v89, v89
	v_exp_f32_e32 v90, v90
	v_exp_f32_e32 v91, v91
	v_exp_f32_e32 v92, v92
	v_exp_f32_e32 v93, v93
	v_exp_f32_e32 v94, v94
	v_exp_f32_e32 v95, v95
	v_pk_add_f32 v[172:173], v[76:77], v[78:79]
	v_pk_add_f32 v[174:175], v[80:81], v[82:83]
	v_pk_add_f32 v[172:173], v[172:173], v[88:89]
	v_pk_add_f32 v[174:175], v[174:175], v[90:91]
	v_pk_add_f32 v[172:173], v[172:173], v[92:93]
	v_pk_add_f32 v[174:175], v[174:175], v[94:95]
	v_pk_add_f32 v[172:173], v[172:173], v[174:175]
	v_add_f32_e32 v147, v172, v173
	s_cbranch_execz .LBB0_1077

.LBB0_1068:
	v_cvt_pk_bf16_f32 v74, v80, v81
	v_cvt_pk_bf16_f32 v75, v82, v83
	ds_read_b64_tr_b16 v[82:83], v236 offset:29952
	ds_read_b64_tr_b16 v[80:81], v236 offset:27648
	ds_read_b64_tr_b16 v[84:85], v236 offset:27680
	v_cvt_pk_bf16_f32 v72, v76, v77
	v_cvt_pk_bf16_f32 v73, v78, v79
	v_cvt_pk_bf16_f32 v76, v96, v97
	v_cvt_pk_bf16_f32 v77, v98, v99
	v_cvt_pk_bf16_f32 v78, v100, v101
	v_cvt_pk_bf16_f32 v79, v102, v103
	s_waitcnt lgkmcnt(1)
	v_mfma_f32_16x16x32_bf16 v[56:59], v[80:83], v[72:75], v[56:59]
	ds_read_b64_tr_b16 v[86:87], v236 offset:29984
	v_cvt_pk_bf16_f32 v68, v88, v89
	v_cvt_pk_bf16_f32 v69, v90, v91
	v_mfma_f32_16x16x32_bf16 v[40:43], v[80:83], v[76:79], v[40:43]
	ds_read_b64_tr_b16 v[80:81], v236 offset:27712
	ds_read_b64_tr_b16 v[82:83], v236 offset:30016
	v_cvt_pk_bf16_f32 v70, v92, v93
	v_cvt_pk_bf16_f32 v71, v94, v95
	s_waitcnt lgkmcnt(0)
	v_mfma_f32_16x16x32_bf16 v[52:55], v[80:83], v[72:75], v[52:55]
	v_cvt_pk_bf16_f32 v64, v104, v105
	v_cvt_pk_bf16_f32 v65, v106, v107
	v_cvt_pk_bf16_f32 v66, v108, v109
	v_mfma_f32_16x16x32_bf16 v[36:39], v[80:83], v[76:79], v[36:39]
	ds_read_b64_tr_b16 v[80:81], v236 offset:27744
	ds_read_b64_tr_b16 v[82:83], v236 offset:30048
	v_cvt_pk_bf16_f32 v67, v110, v111
	v_add_f32_e32 v135, v147, v135
	v_mfma_f32_16x16x32_bf16 v[60:63], v[84:87], v[72:75], v[60:63]
	v_add_f32_e32 v131, v145, v131
	s_waitcnt lgkmcnt(0)
	v_mfma_f32_16x16x32_bf16 v[44:47], v[80:83], v[72:75], v[44:47]
	ds_read_b64_tr_b16 v[72:73], v236 offset:32256
	ds_read_b64_tr_b16 v[74:75], v236 offset:34560
	s_waitcnt lgkmcnt(0)
	v_mfma_f32_16x16x32_bf16 v[56:59], v[72:75], v[68:71], v[56:59]
	v_mfma_f32_16x16x32_bf16 v[40:43], v[72:75], v[64:67], v[40:43]
	ds_read_b64_tr_b16 v[72:73], v236 offset:32288
	ds_read_b64_tr_b16 v[74:75], v236 offset:34592
	v_mfma_f32_16x16x32_bf16 v[48:51], v[84:87], v[76:79], v[48:51]
	s_waitcnt lgkmcnt(0)
	v_mfma_f32_16x16x32_bf16 v[60:63], v[72:75], v[68:71], v[60:63]
	v_mfma_f32_16x16x32_bf16 v[48:51], v[72:75], v[64:67], v[48:51]
	ds_read_b64_tr_b16 v[72:73], v236 offset:32320
	ds_read_b64_tr_b16 v[74:75], v236 offset:34624
	s_waitcnt lgkmcnt(0)
	v_mfma_f32_16x16x32_bf16 v[52:55], v[72:75], v[68:71], v[52:55]
	v_mfma_f32_16x16x32_bf16 v[36:39], v[72:75], v[64:67], v[36:39]
	ds_read_b64_tr_b16 v[72:73], v236 offset:32352
	ds_read_b64_tr_b16 v[74:75], v236 offset:34656
	v_mfma_f32_16x16x32_bf16 v[32:35], v[80:83], v[76:79], v[32:35]
	s_waitcnt lgkmcnt(0)
	v_mfma_f32_16x16x32_bf16 v[44:47], v[72:75], v[68:71], v[44:47]
	v_mfma_f32_16x16x32_bf16 v[32:35], v[72:75], v[64:67], v[32:35]
	s_branch .LBB0_1070
